# clean_k6 + follower workgroups poll the top-level barrier generation word directly (one hop less per grid barrier)
# baseline (speedup 1.0000x reference)
; __device__ __forceinline__ unsigned xb_ld(unsigned* p)              { return __hip_atomic_load(p, __ATOMIC_RELAXED, __HIP_MEMORY_SCOPE_AGENT); }
; __device__ __forceinline__ unsigned xb_add(unsigned* p, unsigned v) { return __hip_atomic_fetch_add(p, v, __ATOMIC_RELAXED, __HIP_MEMORY_SCOPE_AGENT); }
; #define XB_SPIN(cond, bar) do { unsigned _sp = 0; while (cond) { __builtin_amdgcn_s_sleep(1); \
;     if ((++_sp & 255u) == 0u) { if (xb_ld(&(bar)[XB_TMO])) break; if (_sp > XB_SPIN_CAP) { atomicAdd(&(bar)[XB_TMO], 1u); break; } } } } while (0)
; __device__ __forceinline__ void xcd_barrier(const XcdBarrier& b) {
;     ...
;         const unsigned old = xb_add(&bar[XB_XSUB(b.x)], 1u);
;         const unsigned gen = old / nloc;
;         if (old + 1u == (gen + 1u) * nloc) {
;             __builtin_amdgcn_fence(__ATOMIC_RELEASE, "agent");
;             asm volatile("s_waitcnt vmcnt(0)" ::: "memory");
;             const unsigned og = xb_add(&bar[XB_TOP], 1u);
;             const unsigned tg = og / nx;
;             if (og + 1u == (tg + 1u) * nx) xb_add(&bar[XB_TOPGEN], 1u);
;             else XB_SPIN(xb_ld(&bar[XB_TOPGEN]) == tg, bar);
;             __builtin_amdgcn_fence(__ATOMIC_ACQUIRE, "agent");
;             xb_add(&bar[XB_XGEN(b.x)], 1u);
;             asm volatile("s_waitcnt vmcnt(0)" ::: "memory");
;         } else {
;             XB_SPIN(xb_ld(&bar[XB_XGEN(b.x)]) == gen, bar);
;             __builtin_amdgcn_fence(__ATOMIC_ACQUIRE, "agent");
;             asm volatile("s_waitcnt vmcnt(0)" ::: "memory");
;         }
.LBB0_419:
	s_or_b64 exec, exec, s[8:9]
	v_cvt_f32_u32_e32 v5, v3
	s_waitcnt vmcnt(0)
	v_readfirstlane_b32 s6, v4
	v_sub_u32_e32 v4, 0, v3
	v_rcp_iflag_f32_e32 v5, v5
	v_add_u32_e32 v6, s6, v0
	v_mul_f32_e32 v5, 0x4f7ffffe, v5
	v_cvt_u32_f32_e32 v5, v5
	v_mul_lo_u32 v0, v4, v5
	v_mul_hi_u32 v0, v5, v0
	v_add_u32_e32 v0, v5, v0
	v_mul_hi_u32 v0, v6, v0
	v_mul_lo_u32 v4, v0, v3
	v_sub_u32_e32 v4, v6, v4
	v_add_u32_e32 v5, 1, v0
	v_cmp_ge_u32_e32 vcc, v4, v3
	s_nop 1
	v_cndmask_b32_e32 v0, v0, v5, vcc
	v_sub_u32_e32 v5, v4, v3
	v_cndmask_b32_e32 v4, v4, v5, vcc
	v_add_u32_e32 v5, 1, v0
	v_cmp_ge_u32_e32 vcc, v4, v3
	v_add_u32_e32 v4, 1, v6
	s_nop 0
	v_cndmask_b32_e32 v0, v0, v5, vcc
	v_mul_lo_u32 v5, v3, v0
	v_add_u32_e32 v3, v5, v3
	v_cmp_ne_u32_e32 vcc, v4, v3
	s_and_saveexec_b64 s[6:7], vcc
	s_xor_b64 s[6:7], exec, s[6:7]
	s_cbranch_execz .LBB0_433
	s_waitcnt lgkmcnt(0)
	s_add_u32 s12, s2, 0x7500
	s_addc_u32 s13, s3, 0
	global_load_dword v2, v1, s[12:13] sc1
	s_waitcnt vmcnt(0)
	v_cmp_eq_u32_e32 vcc, v2, v0
	s_and_saveexec_b64 s[8:9], vcc
	s_cbranch_execz .LBB0_432
	s_add_u32 s10, s2, 0x4200
	s_addc_u32 s11, s3, 0
	s_mov_b32 s24, 1
	s_mov_b64 s[14:15], 0
	s_branch .LBB0_423
